# grid barrier: waiting blocks poll the global generation word directly instead of the per-XCD relay word (one fewer dependent memory round trip)
# speedup vs baseline: 1.0108x; 1.0108x over previous
; DI unsigned xb_ld(unsigned* p)              { return __hip_atomic_load(p, __ATOMIC_RELAXED, __HIP_MEMORY_SCOPE_AGENT); }
; DI unsigned xb_add(unsigned* p, unsigned v) { return __hip_atomic_fetch_add(p, v, __ATOMIC_RELAXED, __HIP_MEMORY_SCOPE_AGENT); }
; #define XB_SPIN(cond, bar) do { unsigned _sp = 0; while (cond) { __builtin_amdgcn_s_sleep(1); \
;     if ((++_sp & 255u) == 0u) { if (xb_ld(&(bar)[XB_TMO])) break; if (_sp > XB_SPIN_CAP) { atomicAdd(&(bar)[XB_TMO], 1u); break; } } } } while (0)
; DI void xcd_barrier(const XcdBarrier& b) {
;     asm volatile("s_waitcnt vmcnt(0)" ::: "memory");
;     __syncthreads();
;     if (threadIdx.x == 0) {
;         unsigned* bar = b.bar; asm volatile("" : "+s"(bar));
;         __builtin_amdgcn_s_waitcnt(0);
;         unsigned nloc = b.st[0], nx = b.st[1];
;         if (nloc == 0u) { xcd_barrier_complete(bar, b.x, nloc, nx); b.st[0] = nloc; b.st[1] = nx; }
;         const unsigned old = xb_add(&bar[XB_XSUB(b.x)], 1u);
;         const unsigned gen = old / nloc;
;         if (old + 1u == (gen + 1u) * nloc) {
;             __builtin_amdgcn_fence(__ATOMIC_RELEASE, "agent");
;             asm volatile("s_waitcnt vmcnt(0)" ::: "memory");
;             const unsigned og = xb_add(&bar[XB_TOP], 1u);
;             const unsigned tg = og / nx;
;             if (og + 1u == (tg + 1u) * nx) xb_add(&bar[XB_TOPGEN], 1u);
;             else XB_SPIN(xb_ld(&bar[XB_TOPGEN]) == tg, bar);
;             __builtin_amdgcn_fence(__ATOMIC_ACQUIRE, "agent");
;             xb_add(&bar[XB_XGEN(b.x)], 1u);
;             asm volatile("s_waitcnt vmcnt(0)" ::: "memory");
;         } else {
;             XB_SPIN(xb_ld(&bar[XB_XGEN(b.x)]) == gen, bar);
;             __builtin_amdgcn_fence(__ATOMIC_ACQUIRE, "agent");
;             asm volatile("s_waitcnt vmcnt(0)" ::: "memory");
;         }
.LBB0_574:
	v_readlane_b32 s2, v254, 44
	s_add_u32 s3, s6, s2
	s_addc_u32 s2, s7, 0
	v_mov_b32_e32 v3, s3
	v_add_co_u32_e32 v4, vcc, 0x1000, v3
	v_mov_b32_e32 v3, s2
	s_nop 0
	v_addc_co_u32_e32 v5, vcc, 0, v3, vcc
	flat_atomic_add v4, v[4:5], v177 offset:1024 sc0
	v_cvt_f32_u32_e32 v3, v2
	v_sub_u32_e32 v5, 0, v2
	v_rcp_iflag_f32_e32 v3, v3
	s_nop 0
	v_mul_f32_e32 v3, 0x4f7ffffe, v3
	v_cvt_u32_f32_e32 v3, v3
	v_mul_lo_u32 v5, v5, v3
	v_mul_hi_u32 v5, v3, v5
	v_add_u32_e32 v3, v3, v5
	s_waitcnt vmcnt(0) lgkmcnt(0)
	v_mul_hi_u32 v3, v4, v3
	v_mul_lo_u32 v5, v3, v2
	v_sub_u32_e32 v5, v4, v5
	v_cmp_ge_u32_e32 vcc, v5, v2
	v_add_u32_e32 v6, 1, v3
	s_nop 0
	v_cndmask_b32_e32 v3, v3, v6, vcc
	v_sub_u32_e32 v6, v5, v2
	v_cndmask_b32_e32 v5, v5, v6, vcc
	v_cmp_ge_u32_e32 vcc, v5, v2
	v_add_u32_e32 v5, 1, v3
	v_add_u32_e32 v6, 1, v4
	v_cndmask_b32_e32 v3, v3, v5, vcc
	v_mad_u64_u32 v[4:5], s[8:9], v2, v3, v[2:3]
	v_cmp_ne_u32_e32 vcc, v6, v4
	s_and_saveexec_b64 s[8:9], vcc
	s_xor_b64 s[8:9], exec, s[8:9]
	s_cbranch_execz .LBB0_587
	s_add_u32 s12, s6, 0x3500
	s_addc_u32 s13, s7, 0
	v_mov_b64_e32 v[4:5], s[12:13]
	flat_load_dword v0, v[4:5] sc1
	s_waitcnt vmcnt(0) lgkmcnt(0)
	v_cmp_eq_u32_e32 vcc, v0, v3
	s_and_saveexec_b64 s[10:11], vcc
	s_cbranch_execz .LBB0_586
	s_mov_b32 s24, 1
	s_mov_b64 s[14:15], 0
	s_branch .LBB0_578
